# placement variant: GEMM MFMA segments 8-byte aligned and the attention phase code shifted by 4 bytes (other byte phase)
# speedup vs baseline: 1.0127x; 1.0127x over previous
; #define PG8_STAGE(bufoff, gbase, voff) do { _Pragma("unroll") for (int _i = 0; _i < 2; ++_i) \
;         __builtin_amdgcn_global_load_lds((const unsigned*)((const char*)(gbase) + (voff)[_i]), (LAS unsigned*)(lds + (bufoff) + ldsw + _i * 8192), 16, 0, 0); } while (0)
; #define PG8_LDA(dst, b, h) do { _Pragma("unroll") for (int m = 0; m < 4; ++m) _Pragma("unroll") for (int k = 0; k < 2; ++k) dst[m][k] = *(const LAS bf16x8*)(lds + PG8_SA(b, h) + aoff + m * 2048 + k * 1024); } while (0)
; #define PG8_LDB(dst, b, h) do { _Pragma("unroll") for (int n = 0; n < 2; ++n) _Pragma("unroll") for (int k = 0; k < 2; ++k) dst[n][k] = *(const LAS bf16x8*)(lds + PG8_SB(b, h) + boff + n * 2048 + k * 1024); } while (0)
; #define PG8_MMA(ai, bj, At, Bt) do { __builtin_amdgcn_s_setprio(1); _Pragma("unroll") for (int m = 0; m < 4; ++m) _Pragma("unroll") for (int n = 0; n < 2; ++n) _Pragma("unroll") for (int k = 0; k < 2; ++k) \
;         acc[ai][bj][m][n] = __builtin_amdgcn_mfma_f32_16x16x32_bf16(Bt[n][k], At[m][k], acc[ai][bj][m][n], 0, 0, 0); __builtin_amdgcn_s_setprio(0); } while (0)
; #define PG8_WAIT_V(n) asm volatile("s_waitcnt vmcnt(" #n ")" ::: "memory")
; #define PG8_WAIT_L(n) asm volatile("s_waitcnt lgkmcnt(" #n ")" ::: "memory")
; #define PG8_BAR __builtin_amdgcn_s_barrier()
; #define PG8_SCHED __builtin_amdgcn_sched_barrier(0)
; template <class Epi, class Sched>
; DI void gemm_phase(LAS unsigned char* lds, const Gemm g, const Sched& S, const Epi& E) {
;     ...
;             PG8_LDB(B0, 0, 0); PG8_LDB(B1, 0, 1); PG8_SCHED; PG8_LDA(At, 0, 0); PG8_STAGE(PG8_SA(1, 1), a1 + hstepA, voffA);
;             PG8_WAIT_V(8); PG8_WAIT_L(0); PG8_BAR; PG8_MMA(0, 0, At, B0); PG8_MMA(0, 1, At, B1); PG8_BAR; PG8_SCHED;
;             PG8_LDA(At, 0, 1); PG8_STAGE(PG8_SB(0, 0), b2, voffB); PG8_STAGE(PG8_SB(0, 1), b2 + hstepB, voffB); PG8_STAGE(PG8_SA(0, 0), a2, voffA);
;             PG8_WAIT_V(8); PG8_WAIT_L(0); PG8_BAR; PG8_MMA(1, 0, At, B0); PG8_MMA(1, 1, At, B1); PG8_BAR; PG8_SCHED;
.Lpk3_w1:
	s_waitcnt lgkmcnt(0)
	s_nop 0
	s_barrier
	s_setprio 1
	v_mfma_f32_16x16x32_bf16 v[126:129], v[146:149], v[186:189], v[126:129]
	v_mfma_f32_16x16x32_bf16 v[122:125], v[154:157], v[186:189], v[122:125]
	v_mfma_f32_16x16x32_bf16 v[118:121], v[146:149], v[194:197], v[118:121]
	v_mfma_f32_16x16x32_bf16 v[114:117], v[154:157], v[194:197], v[114:117]
	v_mfma_f32_16x16x32_bf16 v[110:113], v[146:149], v[202:205], v[110:113]
	v_mfma_f32_16x16x32_bf16 v[106:109], v[154:157], v[202:205], v[106:109]
	v_mfma_f32_16x16x32_bf16 v[102:105], v[146:149], v[210:213], v[102:105]
	v_mfma_f32_16x16x32_bf16 v[98:101], v[154:157], v[210:213], v[98:101]
	v_mfma_f32_16x16x32_bf16 v[126:129], v[150:153], v[190:193], v[126:129]
	v_mfma_f32_16x16x32_bf16 v[122:125], v[158:161], v[190:193], v[122:125]
	v_mfma_f32_16x16x32_bf16 v[118:121], v[150:153], v[198:201], v[118:121]
	v_mfma_f32_16x16x32_bf16 v[114:117], v[158:161], v[198:201], v[114:117]
	v_mfma_f32_16x16x32_bf16 v[110:113], v[150:153], v[206:209], v[110:113]
	v_mfma_f32_16x16x32_bf16 v[106:109], v[158:161], v[206:209], v[106:109]
	v_mfma_f32_16x16x32_bf16 v[102:105], v[150:153], v[214:217], v[102:105]
	v_mfma_f32_16x16x32_bf16 v[98:101], v[158:161], v[214:217], v[98:101]
	v_mfma_f32_16x16x32_bf16 v[94:97], v[168:171], v[186:189], v[94:97]
	v_mfma_f32_16x16x32_bf16 v[90:93], v[176:179], v[186:189], v[90:93]
	v_mfma_f32_16x16x32_bf16 v[86:89], v[168:171], v[194:197], v[86:89]
	v_mfma_f32_16x16x32_bf16 v[82:85], v[176:179], v[194:197], v[82:85]
	v_mfma_f32_16x16x32_bf16 v[78:81], v[168:171], v[202:205], v[78:81]
	v_mfma_f32_16x16x32_bf16 v[74:77], v[176:179], v[202:205], v[74:77]
	v_mfma_f32_16x16x32_bf16 v[70:73], v[168:171], v[210:213], v[70:73]
	v_mfma_f32_16x16x32_bf16 v[66:69], v[176:179], v[210:213], v[66:69]
	v_mfma_f32_16x16x32_bf16 v[94:97], v[172:175], v[190:193], v[94:97]
	v_mfma_f32_16x16x32_bf16 v[90:93], v[180:183], v[190:193], v[90:93]
	v_mfma_f32_16x16x32_bf16 v[86:89], v[172:175], v[198:201], v[86:89]
	v_mfma_f32_16x16x32_bf16 v[82:85], v[180:183], v[198:201], v[82:85]
	v_mfma_f32_16x16x32_bf16 v[78:81], v[172:175], v[206:209], v[78:81]
	v_mfma_f32_16x16x32_bf16 v[74:77], v[180:183], v[206:209], v[74:77]
	v_mfma_f32_16x16x32_bf16 v[70:73], v[172:175], v[214:217], v[70:73]
	v_mfma_f32_16x16x32_bf16 v[66:69], v[180:183], v[214:217], v[66:69]
	s_setprio 0
	s_barrier
	s_add_i32 s73, s64, s52
	v_lshl_add_u64 v[218:219], s[46:47], 0, v[132:133]
	s_mov_b32 m0, s73
	ds_read_b128 v[186:189], v167 offset:16384
	ds_read_b128 v[190:193], v167 offset:17408
	ds_read_b128 v[194:197], v167 offset:18432
	ds_read_b128 v[198:201], v167 offset:19456
	ds_read_b128 v[202:205], v167 offset:20480
	ds_read_b128 v[206:209], v167 offset:21504
	ds_read_b128 v[210:213], v167 offset:22528
	ds_read_b128 v[214:217], v167 offset:23552
	global_load_lds_dwordx4 v[218:219], off
	s_add_i32 m0, s73, 0x2000
	s_add_u32 s74, s46, 0x20000
	v_lshl_add_u64 v[220:221], s[46:47], 0, v[136:137]
	s_addc_u32 s75, s47, 0
	s_add_i32 s73, s65, s52
	global_load_lds_dwordx4 v[220:221], off
	v_lshl_add_u64 v[222:223], s[74:75], 0, v[132:133]
	s_mov_b32 m0, s73
	v_lshl_add_u64 v[224:225], s[48:49], 0, v[134:135]
	global_load_lds_dwordx4 v[222:223], off
	v_lshl_add_u64 v[222:223], s[74:75], 0, v[136:137]
	s_add_i32 m0, s73, 0x2000
	s_nop 0
	global_load_lds_dwordx4 v[222:223], off
	v_lshl_add_u64 v[222:223], s[48:49], 0, v[130:131]
	s_mov_b32 m0, s53
	s_nop 0
	global_load_lds_dwordx4 v[222:223], off
	s_mov_b32 m0, s54
	s_nop 0
	global_load_lds_dwordx4 v[224:225], off
	s_cmp_lg_u32 s99, 0
	s_cbranch_scc1 .Lpk3_w2
	s_waitcnt vmcnt(8)
